# HG in-proj tile order balanced further: forget-gate tiles moved from 5-tile blocks to 4-tile blocks
# baseline (speedup 1.0000x reference)
;     __device__ bool next(int i, Unit& u) const {
;     ...
;         const long L = (long)i * G + c; if (L >= (long)nwg * nS) return false;
;         u.s = (int)(L / nwg); int wgid = (int)(L % nwg);
;         { const int q = nwg / NXCD, r = nwg % NXCD, xcd = wgid % NXCD, off = wgid / NXCD; wgid = (xcd < r ? xcd * (q + 1) : r * (q + 1) + (xcd - r) * q) + off; }
;         const int nig = WGM * nN, gid = wgid / nig, fm = gid * WGM, gsz = (nM - fm) < WGM ? (nM - fm) : WGM;
;         u.pm = __builtin_amdgcn_readfirstlane(fm + ((wgid % nig) % gsz)); u.pn = __builtin_amdgcn_readfirstlane((wgid % nig) / gsz); u.s = __builtin_amdgcn_readfirstlane(u.s); u.kb = 0; u.nt = 0; u.full = 0; return true;
.Ltb_lo_a:
	s_and_b32 s18, s5, 7
	s_lshr_b32 s4, s5, 3
	s_and_b32 s19, s4, 31
	s_mul_i32 s22, s18, 10
	s_cmp_lt_u32 s19, 10
	s_cbranch_scc1 .Ltb_qa_a
	s_sub_u32 s19, s19, 10
	s_cmp_lt_u32 s19, 10
	s_cbranch_scc0 .Ltb_qbchk_a
	s_add_u32 s19, s19, s22
	s_add_u32 s19, s19, 10
	s_and_b32 s19, s19, 31
	s_sub_u32 s19, s19, s22
	s_add_u32 s19, s19, 64
	s_and_b32 s19, s19, 0x7f
	s_cmp_eq_u32 s19, s4
	s_cbranch_scc0 .Ltb_done_a
	s_and_b32 s4, s4, 31
	s_sub_u32 s4, s4, 10
	s_lshl_b32 s4, s4, 3
	s_or_b32 s4, s4, s18
	s_or_b32 s5, s4, 0x400
	s_branch .Ltb_done_a
.Ltb_qbchk_a:
	s_sub_u32 s19, s19, 10
	s_cmp_lt_u32 s19, 10
	s_cbranch_scc0 .Ltb_done_a
	s_add_u32 s4, s4, s22
	s_and_b32 s4, s4, 0x7f
	s_lshr_b32 s4, s4, 5
	s_cmp_eq_u32 s4, 2
	s_cbranch_scc0 .Ltb_done_a
	s_add_u32 s4, s19, s22
	s_and_b32 s4, s4, 0x7f
	s_lshr_b32 s4, s4, 5
	s_sub_u32 s4, 1, s4
	s_and_b32 s4, s4, 3
	s_lshl_b32 s4, s4, 5
	s_add_u32 s4, s4, s19
	s_lshl_b32 s4, s4, 3
	s_or_b32 s5, s4, s18
	s_branch .Ltb_done_a
.Ltb_qa_a:
	s_add_u32 s4, s4, s22
	s_and_b32 s4, s4, 0x7f
	s_lshr_b32 s4, s4, 5
	s_cmp_eq_u32 s4, 1
	s_cbranch_scc0 .Ltb_done_a
	s_add_u32 s19, s19, 20
	s_add_u32 s4, s19, s22
	s_and_b32 s4, s4, 0x7f
	s_lshr_b32 s4, s4, 5
	s_sub_u32 s4, 2, s4
	s_and_b32 s4, s4, 3
	s_lshl_b32 s4, s4, 5
	s_add_u32 s4, s4, s19
	s_lshl_b32 s4, s4, 3
	s_or_b32 s5, s4, s18

;     __device__ bool next(int i, Unit& u) const {
;     ...
;         const long L = (long)i * G + c; if (L >= (long)nwg * nS) return false;
;         u.s = (int)(L / nwg); int wgid = (int)(L % nwg);
;         { const int q = nwg / NXCD, r = nwg % NXCD, xcd = wgid % NXCD, off = wgid / NXCD; wgid = (xcd < r ? xcd * (q + 1) : r * (q + 1) + (xcd - r) * q) + off; }
;         const int nig = WGM * nN, gid = wgid / nig, fm = gid * WGM, gsz = (nM - fm) < WGM ? (nM - fm) : WGM;
;         u.pm = __builtin_amdgcn_readfirstlane(fm + ((wgid % nig) % gsz)); u.pn = __builtin_amdgcn_readfirstlane((wgid % nig) / gsz); u.s = __builtin_amdgcn_readfirstlane(u.s); u.kb = 0; u.nt = 0; u.full = 0; return true;
.Ltb_lo_b:
	s_and_b32 s45, s26, 7
	s_lshr_b32 s44, s26, 3
	s_and_b32 s46, s44, 31
	s_mul_i32 s47, s45, 10
	s_cmp_lt_u32 s46, 10
	s_cbranch_scc1 .Ltb_qa_b
	s_sub_u32 s46, s46, 10
	s_cmp_lt_u32 s46, 10
	s_cbranch_scc0 .Ltb_qbchk_b
	s_add_u32 s46, s46, s47
	s_add_u32 s46, s46, 10
	s_and_b32 s46, s46, 31
	s_sub_u32 s46, s46, s47
	s_add_u32 s46, s46, 64
	s_and_b32 s46, s46, 0x7f
	s_cmp_eq_u32 s46, s44
	s_cbranch_scc0 .Ltb_done_b
	s_and_b32 s44, s44, 31
	s_sub_u32 s44, s44, 10
	s_lshl_b32 s44, s44, 3
	s_or_b32 s44, s44, s45
	s_or_b32 s26, s44, 0x400
	s_branch .Ltb_done_b
.Ltb_qbchk_b:
	s_sub_u32 s46, s46, 10
	s_cmp_lt_u32 s46, 10
	s_cbranch_scc0 .Ltb_done_b
	s_add_u32 s44, s44, s47
	s_and_b32 s44, s44, 0x7f
	s_lshr_b32 s44, s44, 5
	s_cmp_eq_u32 s44, 2
	s_cbranch_scc0 .Ltb_done_b
	s_add_u32 s44, s46, s47
	s_and_b32 s44, s44, 0x7f
	s_lshr_b32 s44, s44, 5
	s_sub_u32 s44, 1, s44
	s_and_b32 s44, s44, 3
	s_lshl_b32 s44, s44, 5
	s_add_u32 s44, s44, s46
	s_lshl_b32 s44, s44, 3
	s_or_b32 s26, s44, s45
	s_branch .Ltb_done_b
.Ltb_qa_b:
	s_add_u32 s44, s44, s47
	s_and_b32 s44, s44, 0x7f
	s_lshr_b32 s44, s44, 5
	s_cmp_eq_u32 s44, 1
	s_cbranch_scc0 .Ltb_done_b
	s_add_u32 s46, s46, 20
	s_add_u32 s44, s46, s47
	s_and_b32 s44, s44, 0x7f
	s_lshr_b32 s44, s44, 5
	s_sub_u32 s44, 2, s44
	s_and_b32 s44, s44, 3
	s_lshl_b32 s44, s44, 5
	s_add_u32 s44, s44, s46
	s_lshl_b32 s44, s44, 3
	s_or_b32 s26, s44, s45
